# up-GEMM K-loop: chained LDS-DMA addresses via in-place bumped scalar bases (all 6 GEMM loops now free of 64-bit VALU address adds)
# speedup vs baseline: 1.0116x; 1.0035x over previous
; #define PG8_STAGE(bufoff, gbase, voff) do { _Pragma("unroll") for (int _i = 0; _i < 2; ++_i) \
;         __builtin_amdgcn_global_load_lds((const unsigned*)((const char*)(gbase) + (voff)[_i]), (LAS unsigned*)(lds + (bufoff) + ldsw + _i * 8192), 16, 0, 0); } while (0)
; #define PG8_LDA(dst, b, h) do { _Pragma("unroll") for (int m = 0; m < 4; ++m) _Pragma("unroll") for (int k = 0; k < 2; ++k) dst[m][k] = *(const LAS bf16x8*)(lds + PG8_SA(b, h) + aoff + m * 2048 + k * 1024); } while (0)
; #define PG8_LDB(dst, b, h) do { _Pragma("unroll") for (int n = 0; n < 2; ++n) _Pragma("unroll") for (int k = 0; k < 2; ++k) dst[n][k] = *(const LAS bf16x8*)(lds + PG8_SB(b, h) + boff + n * 2048 + k * 1024); } while (0)
; #define PG8_MMA(ai, bj, At, Bt) do { __builtin_amdgcn_s_setprio(1); _Pragma("unroll") for (int m = 0; m < 4; ++m) _Pragma("unroll") for (int n = 0; n < 2; ++n) _Pragma("unroll") for (int k = 0; k < 2; ++k) \
;         acc[ai][bj][m][n] = __builtin_amdgcn_mfma_f32_16x16x32_bf16(Bt[n][k], At[m][k], acc[ai][bj][m][n], 0, 0, 0); __builtin_amdgcn_s_setprio(0); } while (0)
; #define PG8_WAIT_V(n) asm volatile("s_waitcnt vmcnt(" #n ")" ::: "memory")
; #define PG8_WAIT_L(n) asm volatile("s_waitcnt lgkmcnt(" #n ")" ::: "memory")
; #define PG8_BAR __builtin_amdgcn_s_barrier()
; #define PG8_SCHED __builtin_amdgcn_sched_barrier(0)
; template <class Epi, class Sched, bool AREMAP>
; __device__ __forceinline__ void gemm_phase(LAS unsigned char* lds, const Gemm g, const Sched& S, const Epi& E, int wv) {
;     ...
;             const char* a1 = cA + (size_t)(t + 1) * kstep;
;             const char* a2 = last ? nA : cA + (size_t)(t + 2) * kstep; const char* b2 = last ? nB : cB + (size_t)(t + 2) * kstep;
;             const char* a3 = a2 + kstep; const char* b3 = b2 + kstep;
;             PG8_LDB(B0, 0, 0); PG8_SCHED; PG8_LDA(At, 0, 0); PG8_STAGE(PG8_SA(1, 1), a1 + hstepA, voffA);
;             PG8_WAIT_L(8); PG8_BAR; PG8_WAIT_L(0); PG8_MMA(0, 0, At, B0); PG8_BAR; PG8_SCHED;
;             PG8_LDB(B1, 0, 1); PG8_STAGE(PG8_SB(0, 0), b2, voffB);
;             PG8_BAR; PG8_WAIT_L(0); PG8_MMA(0, 1, At, B1); PG8_BAR;
;             PG8_LDA(At, 0, 1); PG8_STAGE(PG8_SA(0, 0), a2, voffA);
;             PG8_BAR; PG8_WAIT_L(0); PG8_MMA(1, 0, At, B0); PG8_BAR; PG8_SCHED;
;             PG8_STAGE(PG8_SB(0, 1), b2 + hstepB, voffB);
;             PG8_WAIT_V(6); PG8_BAR; PG8_MMA(1, 1, At, B1); PG8_BAR;
.LBB0_619:
	s_add_u32 s38, s78, 0xfffc0080
	s_addc_u32 s39, s79, -1
	s_add_i32 s33, 0, 0x10000
	v_add_u32_e32 v142, s33, v1
	ds_read_b128 v[130:133], v142
	ds_read_b128 v[134:137], v142 offset:1024
	ds_read_b128 v[138:141], v142 offset:2048
	ds_read_b128 v[142:145], v142 offset:3072
	s_cmp_eq_u32 vcc_hi, 28
	s_cselect_b32 s97, s46, s39
	s_cselect_b32 s96, s47, s38
	s_cselect_b32 s81, s63, vcc_lo
	s_cselect_b32 s80, s67, s77
	s_add_i32 m0, s10, 0xc000
	ds_read_b128 v[146:149], v183
	ds_read_b128 v[150:153], v183 offset:1024
	ds_read_b128 v[170:173], v183 offset:2048
	ds_read_b128 v[174:177], v183 offset:3072
	ds_read_b128 v[184:187], v183 offset:4096
	ds_read_b128 v[192:195], v183 offset:5120
	ds_read_b128 v[196:199], v183 offset:6144
	ds_read_b128 v[200:203], v183 offset:7168
	global_load_lds_dwordx4 v168, s[78:79]
	s_add_i32 m0, s10, 0xe000
	s_nop 0
	global_load_lds_dwordx4 v166, s[78:79]
	s_waitcnt lgkmcnt(8)
	s_barrier
	s_waitcnt lgkmcnt(0)
	s_waitcnt lgkmcnt(0)
	v_mfma_f32_16x16x32_bf16 v[126:129], v[130:133], v[146:149], v[126:129]
	v_mfma_f32_16x16x32_bf16 v[62:65], v[138:141], v[146:149], v[62:65]
	v_mfma_f32_16x16x32_bf16 v[118:121], v[130:133], v[170:173], v[118:121]
	v_mfma_f32_16x16x32_bf16 v[54:57], v[138:141], v[170:173], v[54:57]
	v_mfma_f32_16x16x32_bf16 v[110:113], v[130:133], v[184:187], v[110:113]
	v_mfma_f32_16x16x32_bf16 v[46:49], v[138:141], v[184:187], v[46:49]
	v_mfma_f32_16x16x32_bf16 v[102:105], v[130:133], v[196:199], v[102:105]
	v_mfma_f32_16x16x32_bf16 v[38:41], v[138:141], v[196:199], v[38:41]
	v_mfma_f32_16x16x32_bf16 v[126:129], v[134:137], v[150:153], v[126:129]
	v_mfma_f32_16x16x32_bf16 v[62:65], v[142:145], v[150:153], v[62:65]
	v_mfma_f32_16x16x32_bf16 v[118:121], v[134:137], v[174:177], v[118:121]
	v_mfma_f32_16x16x32_bf16 v[54:57], v[142:145], v[174:177], v[54:57]
	v_mfma_f32_16x16x32_bf16 v[110:113], v[134:137], v[192:195], v[110:113]
	v_mfma_f32_16x16x32_bf16 v[46:49], v[142:145], v[192:195], v[46:49]
	v_mfma_f32_16x16x32_bf16 v[102:105], v[134:137], v[200:203], v[102:105]
	v_mfma_f32_16x16x32_bf16 v[38:41], v[142:145], v[200:203], v[38:41]
	s_barrier
	s_add_i32 s58, 0, 0x14000
	v_add_u32_e32 v178, s58, v1
	s_add_i32 s33, s33, s91
	ds_read_b128 v[204:207], v178
	ds_read_b128 v[208:211], v178 offset:1024
	ds_read_b128 v[212:215], v178 offset:2048
	ds_read_b128 v[216:219], v178 offset:3072
	s_mov_b32 m0, s33
	s_nop 0
	global_load_lds_dwordx4 v158, s[80:81]
	s_add_i32 m0, s33, 0x2000
	s_nop 0
	global_load_lds_dwordx4 v154, s[80:81]
	s_add_u32 s80, s80, 0x80
	s_addc_u32 s81, s81, 0
	s_barrier
	s_waitcnt lgkmcnt(0)
	s_waitcnt lgkmcnt(0)
	v_mfma_f32_16x16x32_bf16 v[122:125], v[204:207], v[146:149], v[122:125]
	v_mfma_f32_16x16x32_bf16 v[58:61], v[212:215], v[146:149], v[58:61]
	v_mfma_f32_16x16x32_bf16 v[114:117], v[204:207], v[170:173], v[114:117]
	v_mfma_f32_16x16x32_bf16 v[50:53], v[212:215], v[170:173], v[50:53]
	v_mfma_f32_16x16x32_bf16 v[106:109], v[204:207], v[184:187], v[106:109]
	v_mfma_f32_16x16x32_bf16 v[42:45], v[212:215], v[184:187], v[42:45]
	v_mfma_f32_16x16x32_bf16 v[98:101], v[204:207], v[196:199], v[98:101]
	v_mfma_f32_16x16x32_bf16 v[34:37], v[212:215], v[196:199], v[34:37]
	v_mfma_f32_16x16x32_bf16 v[122:125], v[208:211], v[150:153], v[122:125]
	v_mfma_f32_16x16x32_bf16 v[58:61], v[216:219], v[150:153], v[58:61]
	v_mfma_f32_16x16x32_bf16 v[114:117], v[208:211], v[174:177], v[114:117]
	v_mfma_f32_16x16x32_bf16 v[50:53], v[216:219], v[174:177], v[50:53]
	v_mfma_f32_16x16x32_bf16 v[106:109], v[208:211], v[192:195], v[106:109]
	v_mfma_f32_16x16x32_bf16 v[42:45], v[216:219], v[192:195], v[42:45]
	v_mfma_f32_16x16x32_bf16 v[98:101], v[208:211], v[200:203], v[98:101]
	v_mfma_f32_16x16x32_bf16 v[34:37], v[216:219], v[200:203], v[34:37]
	s_mov_b32 m0, s10
	s_barrier
	ds_read_b128 v[146:149], v183 offset:16384
	ds_read_b128 v[150:153], v183 offset:17408
	ds_read_b128 v[170:173], v183 offset:18432
	ds_read_b128 v[174:177], v183 offset:19456
	ds_read_b128 v[184:187], v183 offset:20480
	ds_read_b128 v[192:195], v183 offset:21504
	ds_read_b128 v[196:199], v183 offset:22528
	ds_read_b128 v[200:203], v183 offset:23552
	global_load_lds_dwordx4 v160, s[96:97]
	s_mov_b32 m0, s11
	s_nop 0
	global_load_lds_dwordx4 v156, s[96:97]
	s_add_u32 s96, s96, 0x80
	s_addc_u32 s97, s97, 0
	s_barrier
	s_waitcnt lgkmcnt(0)
	s_waitcnt lgkmcnt(0)
	v_mfma_f32_16x16x32_bf16 v[94:97], v[130:133], v[146:149], v[94:97]
	v_mfma_f32_16x16x32_bf16 v[30:33], v[138:141], v[146:149], v[30:33]
	v_mfma_f32_16x16x32_bf16 v[86:89], v[130:133], v[170:173], v[86:89]
	v_mfma_f32_16x16x32_bf16 v[22:25], v[138:141], v[170:173], v[22:25]
	v_mfma_f32_16x16x32_bf16 v[78:81], v[130:133], v[184:187], v[78:81]
	v_mfma_f32_16x16x32_bf16 v[14:17], v[138:141], v[184:187], v[14:17]
	v_mfma_f32_16x16x32_bf16 v[70:73], v[130:133], v[196:199], v[70:73]
	v_mfma_f32_16x16x32_bf16 v[6:9], v[138:141], v[196:199], v[6:9]
	v_mfma_f32_16x16x32_bf16 v[94:97], v[134:137], v[150:153], v[94:97]
	v_mfma_f32_16x16x32_bf16 v[30:33], v[142:145], v[150:153], v[30:33]
	v_mfma_f32_16x16x32_bf16 v[86:89], v[134:137], v[174:177], v[86:89]
	v_mfma_f32_16x16x32_bf16 v[22:25], v[142:145], v[174:177], v[22:25]
	v_mfma_f32_16x16x32_bf16 v[78:81], v[134:137], v[192:195], v[78:81]
	v_mfma_f32_16x16x32_bf16 v[14:17], v[142:145], v[192:195], v[14:17]
	v_mfma_f32_16x16x32_bf16 v[70:73], v[134:137], v[200:203], v[70:73]
	v_mfma_f32_16x16x32_bf16 v[6:9], v[142:145], v[200:203], v[6:9]
	s_barrier
	s_add_u32 s38, s80, 0x7ff80
	s_addc_u32 s39, s81, 0
	s_add_i32 s33, s58, s91
	s_mov_b32 m0, s33
	s_nop 0
	global_load_lds_dwordx4 v158, s[38:39]
	s_add_i32 m0, s33, 0x2000
	s_nop 0
	global_load_lds_dwordx4 v154, s[38:39]
	s_waitcnt vmcnt(6)
	s_barrier
; #define PG8_STAGE(bufoff, gbase, voff) do { _Pragma("unroll") for (int _i = 0; _i < 2; ++_i) \
;         __builtin_amdgcn_global_load_lds((const unsigned*)((const char*)(gbase) + (voff)[_i]), (LAS unsigned*)(lds + (bufoff) + ldsw + _i * 8192), 16, 0, 0); } while (0)
; #define PG8_LDA(dst, b, h) do { _Pragma("unroll") for (int m = 0; m < 4; ++m) _Pragma("unroll") for (int k = 0; k < 2; ++k) dst[m][k] = *(const LAS bf16x8*)(lds + PG8_SA(b, h) + aoff + m * 2048 + k * 1024); } while (0)
; #define PG8_LDB(dst, b, h) do { _Pragma("unroll") for (int n = 0; n < 2; ++n) _Pragma("unroll") for (int k = 0; k < 2; ++k) dst[n][k] = *(const LAS bf16x8*)(lds + PG8_SB(b, h) + boff + n * 2048 + k * 1024); } while (0)
; #define PG8_MMA(ai, bj, At, Bt) do { __builtin_amdgcn_s_setprio(1); _Pragma("unroll") for (int m = 0; m < 4; ++m) _Pragma("unroll") for (int n = 0; n < 2; ++n) _Pragma("unroll") for (int k = 0; k < 2; ++k) \
;         acc[ai][bj][m][n] = __builtin_amdgcn_mfma_f32_16x16x32_bf16(Bt[n][k], At[m][k], acc[ai][bj][m][n], 0, 0, 0); __builtin_amdgcn_s_setprio(0); } while (0)
; #define PG8_WAIT_V(n) asm volatile("s_waitcnt vmcnt(" #n ")" ::: "memory")
; #define PG8_WAIT_L(n) asm volatile("s_waitcnt lgkmcnt(" #n ")" ::: "memory")
; #define PG8_BAR __builtin_amdgcn_s_barrier()
; #define PG8_SCHED __builtin_amdgcn_sched_barrier(0)
; template <class Epi, class Sched, bool AREMAP>
; __device__ __forceinline__ void gemm_phase(LAS unsigned char* lds, const Gemm g, const Sched& S, const Epi& E, int wv) {
;     ...
;             PG8_WAIT_V(6); PG8_BAR; PG8_MMA(1, 1, At, B1); PG8_BAR;
;             PG8_LDB(B0, 1, 0); PG8_SCHED; PG8_LDA(At, 1, 0); PG8_STAGE(PG8_SA(0, 1), a2 + hstepA, voffA);
;             PG8_WAIT_L(8); PG8_BAR; PG8_WAIT_L(0); PG8_MMA(0, 0, At, B0); PG8_BAR; PG8_SCHED;
;             PG8_LDB(B1, 1, 1); PG8_STAGE(PG8_SB(1, 0), b3, voffB);
;             PG8_BAR; PG8_WAIT_L(0); PG8_MMA(0, 1, At, B1); PG8_BAR;
;             PG8_LDA(At, 1, 1); PG8_STAGE(PG8_SA(1, 0), a3, voffA);
	v_mfma_f32_16x16x32_bf16 v[90:93], v[204:207], v[146:149], v[90:93]
	v_mfma_f32_16x16x32_bf16 v[26:29], v[212:215], v[146:149], v[26:29]
	v_mfma_f32_16x16x32_bf16 v[82:85], v[204:207], v[170:173], v[82:85]
	v_mfma_f32_16x16x32_bf16 v[18:21], v[212:215], v[170:173], v[18:21]
	v_mfma_f32_16x16x32_bf16 v[74:77], v[204:207], v[184:187], v[74:77]
	v_mfma_f32_16x16x32_bf16 v[10:13], v[212:215], v[184:187], v[10:13]
	v_mfma_f32_16x16x32_bf16 v[66:69], v[204:207], v[196:199], v[66:69]
	v_mfma_f32_16x16x32_bf16 v[2:5], v[212:215], v[196:199], v[2:5]
	v_mfma_f32_16x16x32_bf16 v[90:93], v[208:211], v[150:153], v[90:93]
	v_mfma_f32_16x16x32_bf16 v[26:29], v[216:219], v[150:153], v[26:29]
	v_mfma_f32_16x16x32_bf16 v[82:85], v[208:211], v[174:177], v[82:85]
	v_mfma_f32_16x16x32_bf16 v[18:21], v[216:219], v[174:177], v[18:21]
	v_mfma_f32_16x16x32_bf16 v[74:77], v[208:211], v[192:195], v[74:77]
	v_mfma_f32_16x16x32_bf16 v[10:13], v[216:219], v[192:195], v[10:13]
	v_mfma_f32_16x16x32_bf16 v[66:69], v[208:211], v[200:203], v[66:69]
	v_mfma_f32_16x16x32_bf16 v[2:5], v[216:219], v[200:203], v[2:5]
	s_add_i32 s33, 0, 0x18000
	v_add_u32_e32 v142, s33, v1
	s_barrier
	ds_read_b128 v[130:133], v142
	ds_read_b128 v[134:137], v142 offset:1024
	ds_read_b128 v[138:141], v142 offset:2048
	ds_read_b128 v[142:145], v142 offset:3072
	s_add_u32 s38, s96, 0x3ff80
	s_addc_u32 s39, s97, 0
	s_mov_b32 m0, s12
	ds_read_b128 v[146:149], v183 offset:32768
	ds_read_b128 v[150:153], v183 offset:33792
	ds_read_b128 v[170:173], v183 offset:34816
	ds_read_b128 v[174:177], v183 offset:35840
	ds_read_b128 v[184:187], v183 offset:36864
	ds_read_b128 v[192:195], v183 offset:37888
	ds_read_b128 v[196:199], v183 offset:38912
	ds_read_b128 v[200:203], v183 offset:39936
	global_load_lds_dwordx4 v160, s[38:39]
	s_mov_b32 m0, s13
	s_nop 0
	global_load_lds_dwordx4 v156, s[38:39]
	s_waitcnt lgkmcnt(8)
	s_barrier
	s_waitcnt lgkmcnt(0)
	s_waitcnt lgkmcnt(0)
	v_mfma_f32_16x16x32_bf16 v[126:129], v[130:133], v[146:149], v[126:129]
	v_mfma_f32_16x16x32_bf16 v[62:65], v[138:141], v[146:149], v[62:65]
	v_mfma_f32_16x16x32_bf16 v[118:121], v[130:133], v[170:173], v[118:121]
	v_mfma_f32_16x16x32_bf16 v[54:57], v[138:141], v[170:173], v[54:57]
	v_mfma_f32_16x16x32_bf16 v[110:113], v[130:133], v[184:187], v[110:113]
	v_mfma_f32_16x16x32_bf16 v[46:49], v[138:141], v[184:187], v[46:49]
	v_mfma_f32_16x16x32_bf16 v[102:105], v[130:133], v[196:199], v[102:105]
	v_mfma_f32_16x16x32_bf16 v[38:41], v[138:141], v[196:199], v[38:41]
	v_mfma_f32_16x16x32_bf16 v[126:129], v[134:137], v[150:153], v[126:129]
	v_mfma_f32_16x16x32_bf16 v[62:65], v[142:145], v[150:153], v[62:65]
	v_mfma_f32_16x16x32_bf16 v[118:121], v[134:137], v[174:177], v[118:121]
	v_mfma_f32_16x16x32_bf16 v[54:57], v[142:145], v[174:177], v[54:57]
	v_mfma_f32_16x16x32_bf16 v[110:113], v[134:137], v[192:195], v[110:113]
	v_mfma_f32_16x16x32_bf16 v[46:49], v[142:145], v[192:195], v[46:49]
	v_mfma_f32_16x16x32_bf16 v[102:105], v[134:137], v[200:203], v[102:105]
	v_mfma_f32_16x16x32_bf16 v[38:41], v[142:145], v[200:203], v[38:41]
	s_barrier
	s_add_i32 s58, 0, 0x1c000
	s_add_i32 s33, s33, s91
	v_add_u32_e32 v216, s58, v1
	s_mov_b32 m0, s33
	ds_read_b128 v[204:207], v216
	ds_read_b128 v[208:211], v216 offset:1024
	ds_read_b128 v[212:215], v216 offset:2048
	ds_read_b128 v[216:219], v216 offset:3072
	global_load_lds_dwordx4 v158, s[80:81]
	s_add_i32 m0, s33, 0x2000
	s_nop 0
	global_load_lds_dwordx4 v154, s[80:81]
	s_barrier
	s_waitcnt lgkmcnt(0)
	s_waitcnt lgkmcnt(0)
	v_mfma_f32_16x16x32_bf16 v[122:125], v[204:207], v[146:149], v[122:125]
	v_mfma_f32_16x16x32_bf16 v[58:61], v[212:215], v[146:149], v[58:61]
	v_mfma_f32_16x16x32_bf16 v[114:117], v[204:207], v[170:173], v[114:117]
	v_mfma_f32_16x16x32_bf16 v[50:53], v[212:215], v[170:173], v[50:53]
	v_mfma_f32_16x16x32_bf16 v[106:109], v[204:207], v[184:187], v[106:109]
	v_mfma_f32_16x16x32_bf16 v[42:45], v[212:215], v[184:187], v[42:45]
	v_mfma_f32_16x16x32_bf16 v[98:101], v[204:207], v[196:199], v[98:101]
	v_mfma_f32_16x16x32_bf16 v[34:37], v[212:215], v[196:199], v[34:37]
	v_mfma_f32_16x16x32_bf16 v[122:125], v[208:211], v[150:153], v[122:125]
	v_mfma_f32_16x16x32_bf16 v[58:61], v[216:219], v[150:153], v[58:61]
	v_mfma_f32_16x16x32_bf16 v[114:117], v[208:211], v[174:177], v[114:117]
	v_mfma_f32_16x16x32_bf16 v[50:53], v[216:219], v[174:177], v[50:53]
	v_mfma_f32_16x16x32_bf16 v[106:109], v[208:211], v[192:195], v[106:109]
	v_mfma_f32_16x16x32_bf16 v[42:45], v[216:219], v[192:195], v[42:45]
	v_mfma_f32_16x16x32_bf16 v[98:101], v[208:211], v[200:203], v[98:101]
	v_mfma_f32_16x16x32_bf16 v[34:37], v[216:219], v[200:203], v[34:37]
	s_mov_b32 m0, s14
	s_barrier
	ds_read_b128 v[146:149], v183 offset:49152
	ds_read_b128 v[150:153], v183 offset:50176
	ds_read_b128 v[170:173], v183 offset:51200
	ds_read_b128 v[174:177], v183 offset:52224
	ds_read_b128 v[184:187], v183 offset:53248
	ds_read_b128 v[192:195], v183 offset:54272
	ds_read_b128 v[196:199], v183 offset:55296
	ds_read_b128 v[200:203], v183 offset:56320
	global_load_lds_dwordx4 v160, s[96:97]
	s_mov_b32 m0, s15
	s_nop 0
	global_load_lds_dwordx4 v156, s[96:97]
	s_barrier
; #define PG8_STAGE(bufoff, gbase, voff) do { _Pragma("unroll") for (int _i = 0; _i < 2; ++_i) \
;         __builtin_amdgcn_global_load_lds((const unsigned*)((const char*)(gbase) + (voff)[_i]), (LAS unsigned*)(lds + (bufoff) + ldsw + _i * 8192), 16, 0, 0); } while (0)
; #define PG8_MMA(ai, bj, At, Bt) do { __builtin_amdgcn_s_setprio(1); _Pragma("unroll") for (int m = 0; m < 4; ++m) _Pragma("unroll") for (int n = 0; n < 2; ++n) _Pragma("unroll") for (int k = 0; k < 2; ++k) \
;         acc[ai][bj][m][n] = __builtin_amdgcn_mfma_f32_16x16x32_bf16(Bt[n][k], At[m][k], acc[ai][bj][m][n], 0, 0, 0); __builtin_amdgcn_s_setprio(0); } while (0)
; #define PG8_WAIT_V(n) asm volatile("s_waitcnt vmcnt(" #n ")" ::: "memory")
; #define PG8_WAIT_L(n) asm volatile("s_waitcnt lgkmcnt(" #n ")" ::: "memory")
; #define PG8_BAR __builtin_amdgcn_s_barrier()
; #define PG8_SCHED __builtin_amdgcn_sched_barrier(0)
; template <class Epi, class Sched, bool AREMAP>
; __device__ __forceinline__ void gemm_phase(LAS unsigned char* lds, const Gemm g, const Sched& S, const Epi& E, int wv) {
;     ...
;         for (int t = 0; t < nt; t += 2) {
;     ...
;             PG8_BAR; PG8_WAIT_L(0); PG8_MMA(1, 0, At, B0); PG8_BAR; PG8_SCHED;
;             PG8_STAGE(PG8_SB(1, 1), b3 + hstepB, voffB);
;             PG8_WAIT_V(6); PG8_BAR; PG8_MMA(1, 1, At, B1); PG8_BAR;
;         }
	s_waitcnt lgkmcnt(0)
	s_waitcnt lgkmcnt(0)
	v_mfma_f32_16x16x32_bf16 v[94:97], v[130:133], v[146:149], v[94:97]
	v_mfma_f32_16x16x32_bf16 v[30:33], v[138:141], v[146:149], v[30:33]
	v_mfma_f32_16x16x32_bf16 v[86:89], v[130:133], v[170:173], v[86:89]
	v_mfma_f32_16x16x32_bf16 v[22:25], v[138:141], v[170:173], v[22:25]
	v_mfma_f32_16x16x32_bf16 v[78:81], v[130:133], v[184:187], v[78:81]
	v_mfma_f32_16x16x32_bf16 v[14:17], v[138:141], v[184:187], v[14:17]
	v_mfma_f32_16x16x32_bf16 v[70:73], v[130:133], v[196:199], v[70:73]
	v_mfma_f32_16x16x32_bf16 v[6:9], v[138:141], v[196:199], v[6:9]
	v_mfma_f32_16x16x32_bf16 v[94:97], v[134:137], v[150:153], v[94:97]
	v_mfma_f32_16x16x32_bf16 v[30:33], v[142:145], v[150:153], v[30:33]
	v_mfma_f32_16x16x32_bf16 v[86:89], v[134:137], v[174:177], v[86:89]
	v_mfma_f32_16x16x32_bf16 v[22:25], v[142:145], v[174:177], v[22:25]
	v_mfma_f32_16x16x32_bf16 v[78:81], v[134:137], v[192:195], v[78:81]
	v_mfma_f32_16x16x32_bf16 v[14:17], v[142:145], v[192:195], v[14:17]
	v_mfma_f32_16x16x32_bf16 v[70:73], v[134:137], v[200:203], v[70:73]
	v_mfma_f32_16x16x32_bf16 v[6:9], v[142:145], v[200:203], v[6:9]
	s_barrier
	s_add_u32 s38, s80, 0x80000
	s_addc_u32 s39, s81, 0
	s_add_i32 s33, s58, s91
	s_mov_b32 m0, s33
	s_nop 0
	global_load_lds_dwordx4 v158, s[38:39]
	s_add_i32 m0, s33, 0x2000
	s_nop 0
	global_load_lds_dwordx4 v154, s[38:39]
	s_waitcnt vmcnt(6)
	s_barrier
	v_mfma_f32_16x16x32_bf16 v[90:93], v[204:207], v[146:149], v[90:93]
	v_mfma_f32_16x16x32_bf16 v[26:29], v[212:215], v[146:149], v[26:29]
	v_mfma_f32_16x16x32_bf16 v[82:85], v[204:207], v[170:173], v[82:85]
	v_mfma_f32_16x16x32_bf16 v[18:21], v[212:215], v[170:173], v[18:21]
	v_mfma_f32_16x16x32_bf16 v[74:77], v[204:207], v[184:187], v[74:77]
	v_mfma_f32_16x16x32_bf16 v[10:13], v[212:215], v[184:187], v[10:13]
	v_mfma_f32_16x16x32_bf16 v[66:69], v[204:207], v[196:199], v[66:69]
	v_mfma_f32_16x16x32_bf16 v[2:5], v[212:215], v[196:199], v[2:5]
	v_mfma_f32_16x16x32_bf16 v[90:93], v[208:211], v[150:153], v[90:93]
	v_mfma_f32_16x16x32_bf16 v[26:29], v[216:219], v[150:153], v[26:29]
	v_mfma_f32_16x16x32_bf16 v[82:85], v[208:211], v[174:177], v[82:85]
	v_mfma_f32_16x16x32_bf16 v[18:21], v[216:219], v[174:177], v[18:21]
	v_mfma_f32_16x16x32_bf16 v[74:77], v[208:211], v[192:195], v[74:77]
	v_mfma_f32_16x16x32_bf16 v[10:13], v[216:219], v[192:195], v[10:13]
	v_mfma_f32_16x16x32_bf16 v[66:69], v[208:211], v[200:203], v[66:69]
	v_mfma_f32_16x16x32_bf16 v[2:5], v[216:219], v[200:203], v[2:5]
	s_add_i32 vcc_hi, vcc_hi, 2
	s_add_u32 s77, s77, 0x100
	s_addc_u32 vcc_lo, vcc_lo, 0
	s_add_u32 s78, s78, 0x100
	s_addc_u32 s79, s79, 0
	s_cmp_gt_u32 vcc_hi, 29
	s_barrier
	s_cbranch_scc0 .LBB0_619
; __device__ __forceinline__ unsigned cvt_pk_bf16(float lo, float hi) { f32x2_t f = {lo, hi}; bf16x2_t v = __builtin_convertvector(f, bf16x2_t); return __builtin_bit_cast(unsigned, v); }
; __device__ __forceinline__ float sigmoidf_(float x) { return __builtin_amdgcn_rcpf(1.0f + __expf(-x)); }
;     __device__ __forceinline__ void operator()(const f32x4 (&acc)[2][2][4][2], const Unit& u, int wr, int wc, int fr, int fq) const {
;         const int lane = fq * 16 + fr;
;         const int ch0 = u.pn * 128 + wc * 32 + 8 * fq;
;         const int seg = u.pm * 2 + wr, tok0 = seg * 128 + fr;
;         const int src1 = (lane & 48) | ((fr + 15) & 15), src2 = (lane & 48) | ((fr + 14) & 15);
; #pragma unroll
;         for (int n = 0; n < 2; ++n) {
;             const int ch = ch0 + 4 * n;
;             f32x4 wv[3], wg[3];
; #pragma unroll
;             for (int k = 0; k < 3; ++k) { wv[k] = *(const f32x4*)(cw + k * NUP + ch); wg[k] = *(const f32x4*)(cw + k * NUP + DFF + ch); }
;             f32x4 pv1 = {0.f, 0.f, 0.f, 0.f}, pv2 = pv1, pg1 = pv1, pg2 = pv1;
; #pragma unroll
;             for (int q = 0; q < 8; ++q) {
;                 const int ai = q >> 2, m = q & 3;
;                 const f32x4 av = acc[ai][0][m][n], ag = acc[ai][1][m][n];
;                 f32x4 rv1, rv2, rg1, rg2;
; #pragma unroll
;                 for (int j = 0; j < 4; ++j) { rv1[j] = SHI(lane, av[j], src1); rv2[j] = SHI(lane, av[j], src2); rg1[j] = SHI(lane, ag[j], src1); rg2[j] = SHI(lane, ag[j], src2); }
;                 const f32x4 sv1 = fr >= 1 ? rv1 : pv1, sv2 = fr >= 2 ? rv2 : pv2, sg1 = fr >= 1 ? rg1 : pg1, sg2 = fr >= 2 ? rg2 : pg2;
;                 const f32x4 ov = wv[2] * av + wv[1] * sv1 + wv[0] * sv2;
;                 const f32x4 og = wg[2] * ag + wg[1] * sg1 + wg[0] * sg2;
;                 u32x2 w;
;                 w.x = cvt_pk_bf16(og[0] * sigmoidf_(og[0]) * ov[0], og[1] * sigmoidf_(og[1]) * ov[1]);
;                 w.y = cvt_pk_bf16(og[2] * sigmoidf_(og[2]) * ov[2], og[3] * sigmoidf_(og[3]) * ov[3]);
;                 *(u32x2*)(act + (size_t)(tok0 + q * 16) * DFF + ch) = w;
;                 if (q == 0 && fr < 2) { float* hp = halo + ((size_t)seg * 4 + fr) * NUP + ch; *(f32x4*)hp = av; *(f32x4*)(hp + DFF) = ag; }
;                 if (q == 7 && fr >= 14) { float* hp = halo + ((size_t)seg * 4 + (fr - 12)) * NUP + ch; *(f32x4*)hp = av; *(f32x4*)(hp + DFF) = ag; }
	v_lshl_or_b32 v170, s37, 7, v182
	s_lshl_b32 s37, s76, 1
	s_add_i32 s46, s37, s75
	s_ashr_i32 s47, s46, 31
	s_lshl_b64 s[76:77], s[46:47], 2
	v_lshl_add_u64 v[130:131], s[76:77], 0, v[162:163]
	s_mov_b32 s33, 0xb000
	v_ashrrev_i32_e32 v171, 31, v170
	v_lshl_or_b32 v184, s46, 7, v162
	v_mad_u64_u32 v[176:177], s[46:47], v130, s33, 0
	v_lshlrev_b64 v[142:143], 2, v[170:171]
	v_mad_i32_i24 v177, v131, s33, v177
	v_lshl_add_u64 v[130:131], s[24:25], 0, v[142:143]
	v_lshl_add_u64 v[138:139], s[26:27], 0, v[142:143]
	global_load_dwordx4 v[130:133], v[130:131], off
	v_lshl_add_u64 v[144:145], s[30:31], 0, v[142:143]
	global_load_dwordx4 v[146:149], v[138:139], off
	v_lshl_add_u64 v[172:173], s[18:19], 0, v[142:143]
	v_lshl_add_u64 v[138:139], s[28:29], 0, v[142:143]
	global_load_dwordx4 v[150:153], v[144:145], off
	global_load_dwordx4 v[134:137], v[172:173], off
	v_lshl_add_u64 v[142:143], s[34:35], 0, v[142:143]
	global_load_dwordx4 v[138:141], v[138:139], off
	v_mov_b32_dpp v199, v126 row_ror:1 row_mask:0xf bank_mask:0xf
	global_load_dwordx4 v[142:145], v[142:143], off
	v_mov_b32_dpp v204, v127 row_ror:1 row_mask:0xf bank_mask:0xf
	v_mov_b32_dpp v206, v128 row_ror:1 row_mask:0xf bank_mask:0xf
	v_mov_b32_dpp v208, v129 row_ror:1 row_mask:0xf bank_mask:0xf
	v_mov_b32_dpp v196, v126 row_ror:2 row_mask:0xf bank_mask:0xf
	v_mov_b32_dpp v186, v122 row_ror:1 row_mask:0xf bank_mask:0xf
	v_mov_b32_dpp v201, v127 row_ror:2 row_mask:0xf bank_mask:0xf
	v_mov_b32_dpp v198, v123 row_ror:1 row_mask:0xf bank_mask:0xf
	v_mov_b32_dpp v203, v128 row_ror:2 row_mask:0xf bank_mask:0xf
	v_mov_b32_dpp v200, v124 row_ror:1 row_mask:0xf bank_mask:0xf
	v_mov_b32_dpp v207, v129 row_ror:2 row_mask:0xf bank_mask:0xf
	v_mov_b32_dpp v205, v125 row_ror:1 row_mask:0xf bank_mask:0xf
	v_mov_b32_dpp v185, v122 row_ror:2 row_mask:0xf bank_mask:0xf
	v_mov_b32_dpp v187, v123 row_ror:2 row_mask:0xf bank_mask:0xf
	v_mov_b32_dpp v197, v124 row_ror:2 row_mask:0xf bank_mask:0xf
	v_mov_b32_dpp v202, v125 row_ror:2 row_mask:0xf bank_mask:0xf
	s_waitcnt lgkmcnt(0)
	v_cndmask_b32_e64 v175, v204, 0, s[0:1]
	v_cndmask_b32_e64 v174, v199, 0, s[0:1]
	v_cndmask_b32_e64 v179, v208, 0, s[0:1]
	v_cndmask_b32_e64 v178, v206, 0, s[0:1]
	v_cndmask_b32_e64 v193, 0, v201, s[2:3]
	v_cndmask_b32_e64 v192, 0, v196, s[2:3]
	v_cndmask_b32_e64 v195, 0, v207, s[2:3]
	v_cndmask_b32_e64 v194, 0, v203, s[2:3]
	v_cndmask_b32_e64 v211, v198, 0, s[0:1]
	v_cndmask_b32_e64 v210, v186, 0, s[0:1]
	v_cndmask_b32_e64 v213, v205, 0, s[0:1]
	v_cndmask_b32_e64 v212, v200, 0, s[0:1]
	v_cndmask_b32_e64 v215, 0, v187, s[2:3]
	v_cndmask_b32_e64 v214, 0, v185, s[2:3]
	v_cndmask_b32_e64 v217, 0, v202, s[2:3]
	v_cndmask_b32_e64 v216, 0, v197, s[2:3]
	s_movk_i32 s33, 0x2c00
	v_lshl_add_u64 v[176:177], s[22:23], 0, v[176:177]
	v_lshl_add_u64 v[176:177], v[170:171], 2, v[176:177]
	s_waitcnt vmcnt(0)
	v_pk_mul_f32 v[178:179], v[148:149], v[178:179]
	v_pk_mul_f32 v[174:175], v[146:147], v[174:175]
	v_pk_fma_f32 v[178:179], v[128:129], v[152:153], v[178:179]
	v_pk_fma_f32 v[174:175], v[126:127], v[150:151], v[174:175]
	v_pk_fma_f32 v[194:195], v[136:137], v[194:195], v[178:179]
	v_pk_fma_f32 v[174:175], v[134:135], v[192:193], v[174:175]
	v_pk_mul_f32 v[178:179], v[140:141], v[212:213]
	v_pk_mul_f32 v[192:193], v[138:139], v[210:211]
	v_pk_fma_f32 v[178:179], v[124:125], v[144:145], v[178:179]
	v_pk_fma_f32 v[192:193], v[122:123], v[142:143], v[192:193]
	v_pk_fma_f32 v[210:211], v[132:133], v[216:217], v[178:179]
	v_pk_fma_f32 v[178:179], v[130:131], v[214:215], v[192:193]
	s_nop 0
	v_mul_f32_e32 v192, 0xbfb8aa3b, v178
	v_mul_f32_e32 v193, 0xbfb8aa3b, v179
	v_exp_f32_e32 v192, v192
	v_exp_f32_e32 v193, v193
	v_add_f32_e32 v192, 1.0, v192
	v_add_f32_e32 v193, 1.0, v193
	v_rcp_f32_e32 v192, v192
	v_rcp_f32_e32 v193, v193
	s_nop 0
	v_pk_mul_f32 v[178:179], v[178:179], v[192:193]
	s_nop 0
	v_pk_mul_f32 v[174:175], v[174:175], v[178:179]
	s_nop 0
	v_cvt_pk_bf16_f32 v178, v174, v175
	v_mul_f32_e32 v174, 0xbfb8aa3b, v210
	v_mul_f32_e32 v175, 0xbfb8aa3b, v211
	v_exp_f32_e32 v174, v174
	v_exp_f32_e32 v175, v175
	v_add_f32_e32 v174, 1.0, v174
	v_add_f32_e32 v175, 1.0, v175
	v_rcp_f32_e32 v174, v174
	v_rcp_f32_e32 v175, v175
	s_nop 0
	v_pk_mul_f32 v[174:175], v[210:211], v[174:175]
	s_nop 0
	v_pk_mul_f32 v[174:175], v[194:195], v[174:175]
	s_nop 0
	v_cvt_pk_bf16_f32 v179, v174, v175
	v_mov_b64_e32 v[174:175], s[20:21]
	v_mad_i64_i32 v[174:175], s[46:47], v184, s33, v[174:175]
	v_lshl_add_u64 v[174:175], v[170:171], 1, v[174:175]
	global_store_dwordx2 v[174:175], v[178:179], off
	s_and_saveexec_b64 s[78:79], s[4:5]
	s_cbranch_execz .LBB0_622
	global_store_dwordx4 v[176:177], v[126:129], off
	s_nop 1
	v_add_co_u32_e32 v126, vcc, 0x5000, v176
	s_nop 1
	v_addc_co_u32_e32 v127, vcc, 0, v177, vcc
	global_store_dwordx4 v[126:127], v[122:125], off offset:2048
